# phase-12 conv: strip-to-workgroup map changed so each XCD works on 11 adjacent 64-column strips (1408 contiguous bytes per row) instead of every 8th strip
# speedup vs baseline: 1.0110x; 1.0110x over previous
; __device__ __forceinline__ void ffn_conv_item(int tid_in, int b, int strip, bf16_t* h1, const bf16_t* h2, const float* cw, const float* cb, bool st = true) {
;     int tid_ = tid_in; asm volatile("" : "+v"(tid_)); const int tid = tid_, lane = tid & 63, wid = __builtin_amdgcn_readfirstlane(tid >> 6), rl = lane >> 3, cg = lane & 7;
;     const int ch = 64 * strip + 8 * cg;
;     float wg[3][8], wv[3][8], bg[8], bv[8];
; #pragma unroll
;     for (int j = 0; j < 3; ++j) { const f32x4 a = *(const f32x4*)(cw + j * 11264 + ch), c = *(const f32x4*)(cw + j * 11264 + ch + 4), a2 = *(const f32x4*)(cw + j * 11264 + 5632 + ch), c2 = *(const f32x4*)(cw + j * 11264 + 5632 + ch + 4);
; #pragma unroll
;         for (int e = 0; e < 4; ++e) { wg[j][e] = a[e]; wg[j][4 + e] = c[e]; wv[j][e] = a2[e]; wv[j][4 + e] = c2[e]; } }
;     { const f32x4 a = *(const f32x4*)(cb + ch), c = *(const f32x4*)(cb + ch + 4), a2 = *(const f32x4*)(cb + 5632 + ch), c2 = *(const f32x4*)(cb + 5632 + ch + 4);
; #pragma unroll
;       for (int e = 0; e < 4; ++e) { bg[e] = a[e]; bg[4 + e] = c[e]; bv[e] = a2[e]; bv[4 + e] = c2[e]; } }
;     const size_t off0 = ((size_t)b * SEQL + 512 * wid) * 5632 + ch;
;     u32x4 pg = {0u, 0u, 0u, 0u}, pv = {0u, 0u, 0u, 0u};
;     if (wid > 0) { pg = *(const u32x4*)(h1 + off0 + (ptrdiff_t)(rl - 8) * 5632); pv = *(const u32x4*)(h2 + off0 + (ptrdiff_t)(rl - 8) * 5632); }
;     asm volatile("s_waitcnt vmcnt(0)" ::: "memory");
;     __syncthreads();
;     u32x4 cg4[4], cv4[4];
; #pragma unroll
;     for (int j = 0; j < 4; ++j) { cg4[j] = __builtin_nontemporal_load((const u32x4*)(h1 + off0 + (size_t)(8 * j + rl) * 5632)); cv4[j] = __builtin_nontemporal_load((const u32x4*)(h2 + off0 + (size_t)(8 * j + rl) * 5632)); }
; #pragma nounroll
.LBB0_18:
	s_waitcnt lgkmcnt(0)
	s_mul_hi_i32 s9, s8, 0x2e8ba2e9
	s_lshr_b32 s18, s9, 31
	s_ashr_i32 s9, s9, 4
	s_add_i32 s18, s9, s18
	s_mul_i32 s9, s18, 0x58
	s_sub_i32 s9, s8, s9
	s_and_b32 s19, s9, 7
	s_mul_i32 s19, s19, 11
	s_lshr_b32 s9, s9, 3
	s_add_i32 s9, s9, s19
	v_and_b32_e32 v0, 63, v146
	v_lshrrev_b32_e32 v159, 3, v0
	v_and_b32_e32 v160, 7, v0
	v_mul_u32_u24_e32 v159, 0xb0000, v159
	v_lshl_add_u32 v159, v160, 4, v159
	s_lshl_b32 s19, s9, 8
	v_lshl_add_u32 v156, v160, 5, s19
	v_lshlrev_b32_e32 v160, 4, v0
	s_lshl_b32 s12, s58, 14
	v_add_u32_e32 v160, s12, v160
	v_add_u32_e32 v148, 0x5800, v156
	v_add_u32_e32 v149, 0xb000, v156
	v_add_u32_e32 v150, 0x10800, v156
	v_add_u32_e32 v151, 0x16000, v156
	v_add_u32_e32 v152, 0x1b800, v156
	global_load_dwordx4 v[2:5], v156, s[44:45]
	global_load_dwordx4 v[6:9], v156, s[44:45] offset:16
	global_load_dwordx4 v[10:13], v148, s[44:45]
	global_load_dwordx4 v[14:17], v148, s[44:45] offset:16
	global_load_dwordx4 v[18:21], v149, s[44:45]
	global_load_dwordx4 v[22:25], v149, s[44:45] offset:16
	global_load_dwordx4 v[26:29], v150, s[44:45]
	global_load_dwordx4 v[30:33], v150, s[44:45] offset:16
	global_load_dwordx4 v[34:37], v151, s[44:45]
	global_load_dwordx4 v[38:41], v151, s[44:45] offset:16
	global_load_dwordx4 v[42:45], v152, s[44:45]
	global_load_dwordx4 v[46:49], v152, s[44:45] offset:16
	global_load_dwordx4 v[50:53], v156, s[46:47]
	global_load_dwordx4 v[54:57], v156, s[46:47] offset:16
	global_load_dwordx4 v[58:61], v148, s[46:47]
	global_load_dwordx4 v[62:65], v148, s[46:47] offset:16
	s_lshl_b32 s19, s18, 12
	s_lshl_b32 s20, s58, 9
	s_add_i32 s19, s19, s20
	s_mul_i32 s19, s19, 0x2c00
	s_lshl_b32 s20, s9, 7
	s_add_i32 s19, s19, s20
	s_add_u32 s40, s66, 0x4a00000
	s_addc_u32 s41, s67, 0
	s_add_u32 s40, s40, s19
	s_addc_u32 s41, s41, 0
	s_sub_u32 s20, s40, 0x2c00
	s_subb_u32 s21, s41, 0
	s_sub_u32 s22, s40, 0x5800
	s_subb_u32 s23, s41, 0
	s_add_u32 s24, s20, 0xb000000
	s_addc_u32 s25, s21, 0
	s_add_u32 s28, s22, 0xb000000
	s_addc_u32 s29, s23, 0
	v_mov_b32_e32 v98, 0
	v_mov_b32_e32 v99, 0
	v_mov_b32_e32 v100, 0
	v_mov_b32_e32 v101, 0
	v_mov_b32_e32 v102, 0
	v_mov_b32_e32 v103, 0
	v_mov_b32_e32 v104, 0
	v_mov_b32_e32 v105, 0
	v_mov_b32_e32 v106, 0
	v_mov_b32_e32 v107, 0
	v_mov_b32_e32 v108, 0
	v_mov_b32_e32 v109, 0
	v_mov_b32_e32 v110, 0
	v_mov_b32_e32 v111, 0
	v_mov_b32_e32 v112, 0
	v_mov_b32_e32 v113, 0
	s_mov_b64 s[18:19], -1
	s_cmp_lg_u32 s58, 0
	s_cbranch_scc1 .Lcv_hm
	s_mov_b32 s18, 0xffffff00

; __device__ __forceinline__ float sigm(float x) { return 1.f / (1.f + __expf(-x)); }
; __device__ __forceinline__ u32x4 pack8(const float (&f)[8]) { u32x4 w; w.x = pk2(f[0], f[1]); w.y = pk2(f[2], f[3]); w.z = pk2(f[4], f[5]); w.w = pk2(f[6], f[7]); return w; }
; __device__ __forceinline__ void ffn_conv_item(int tid_in, int b, int strip, bf16_t* h1, const bf16_t* h2, const float* cw, const float* cb, bool st = true) {
;     ...
;         for (int j = 0; j < 4; ++j) {
;             const size_t off = off0 + (size_t)(32 * blk + 8 * j + rl) * 5632;
;             const u32x4 cgv = cg4[j], cvv = cv4[j];
;             float xg[8], xv[8], yg[8], yv[8]; unpack8(cgv, xg); unpack8(cvv, xv);
; #pragma unroll
;             for (int e = 0; e < 8; ++e) { yg[e] = bg[e] + wg[2][e] * xg[e]; yv[e] = bv[e] + wv[2][e] * xv[e]; }
; #pragma unroll
;             for (int d = 1; d <= 2; ++d) {
;                 const bool own = (rl + d <= 7); const int src = (lane + 64 - 8 * d) & 63;
;                 const u32x4 sg = own ? cgv : pg, sv = own ? cvv : pv;
;                 u32x4 g, v; g.x = __shfl(sg.x, src); g.y = __shfl(sg.y, src); g.z = __shfl(sg.z, src); g.w = __shfl(sg.w, src);
;                 v.x = __shfl(sv.x, src); v.y = __shfl(sv.y, src); v.z = __shfl(sv.z, src); v.w = __shfl(sv.w, src);
;                 float dg[8], dv[8]; unpack8(g, dg); unpack8(v, dv);
; #pragma unroll
;                 for (int e = 0; e < 8; ++e) { yg[e] += wg[2 - d][e] * dg[e]; yv[e] += wv[2 - d][e] * dv[e]; }
;             }
; #pragma unroll
;             for (int e = 0; e < 8; ++e) yg[e] = yg[e] * sigm(yg[e]) * yv[e];
;             { const u32x4 o_ = pack8(yg); if (st) *(u32x4*)(h1 + off) = o_; else asm volatile("" :: "v"(o_)); }
;             pg = cgv; pv = cvv;
;         }
; #pragma unroll
;         for (int j = 0; j < 4; ++j) { cg4[j] = ng4[j]; cv4[j] = nv4[j]; }
;     }
.Lcv_join7:
	s_add_i32 s9, s9, 1
	s_waitcnt lgkmcnt(2)
	v_lshlrev_b32_e32 v114, 16, v106
	v_and_b32_e32 v115, 0xffff0000, v106
	v_lshlrev_b32_e32 v116, 16, v107
	v_and_b32_e32 v117, 0xffff0000, v107
	v_lshlrev_b32_e32 v118, 16, v108
	v_and_b32_e32 v119, 0xffff0000, v108
	v_lshlrev_b32_e32 v120, 16, v109
	v_and_b32_e32 v121, 0xffff0000, v109
	v_lshlrev_b32_e32 v122, 16, v110
	v_and_b32_e32 v123, 0xffff0000, v110
	v_lshlrev_b32_e32 v124, 16, v111
	v_and_b32_e32 v125, 0xffff0000, v111
	v_lshlrev_b32_e32 v126, 16, v112
	v_and_b32_e32 v127, 0xffff0000, v112
	v_lshlrev_b32_e32 v128, 16, v113
	v_and_b32_e32 v129, 0xffff0000, v113
	v_pk_fma_f32 v[130:131], v[34:35], v[114:115], v[66:67]
	v_pk_fma_f32 v[132:133], v[36:37], v[116:117], v[68:69]
	v_pk_fma_f32 v[134:135], v[38:39], v[118:119], v[70:71]
	v_pk_fma_f32 v[136:137], v[40:41], v[120:121], v[72:73]
	v_pk_fma_f32 v[138:139], v[42:43], v[122:123], v[74:75]
	v_pk_fma_f32 v[140:141], v[44:45], v[124:125], v[76:77]
	v_pk_fma_f32 v[142:143], v[46:47], v[126:127], v[78:79]
	v_pk_fma_f32 v[144:145], v[48:49], v[128:129], v[80:81]
	v_pk_fma_f32 v[66:67], v[18:19], v[114:115], v[82:83]
	v_pk_fma_f32 v[68:69], v[20:21], v[116:117], v[84:85]
	v_pk_fma_f32 v[70:71], v[22:23], v[118:119], v[86:87]
	v_pk_fma_f32 v[72:73], v[24:25], v[120:121], v[88:89]
	v_pk_fma_f32 v[74:75], v[26:27], v[122:123], v[90:91]
	v_pk_fma_f32 v[76:77], v[28:29], v[124:125], v[92:93]
	v_pk_fma_f32 v[78:79], v[30:31], v[126:127], v[94:95]
	v_pk_fma_f32 v[80:81], v[32:33], v[128:129], v[96:97]
	v_pk_fma_f32 v[82:83], v[2:3], v[114:115], v[50:51]
	v_pk_fma_f32 v[84:85], v[4:5], v[116:117], v[52:53]
	v_pk_fma_f32 v[86:87], v[6:7], v[118:119], v[54:55]
	v_pk_fma_f32 v[88:89], v[8:9], v[120:121], v[56:57]
	v_pk_fma_f32 v[90:91], v[10:11], v[122:123], v[58:59]
	v_pk_fma_f32 v[92:93], v[12:13], v[124:125], v[60:61]
	v_pk_fma_f32 v[94:95], v[14:15], v[126:127], v[62:63]
	v_pk_fma_f32 v[96:97], v[16:17], v[128:129], v[64:65]
	v_pk_mul_f32 v[148:149], v[130:131], s[34:35]
	v_pk_mul_f32 v[150:151], v[132:133], s[34:35]
	v_pk_mul_f32 v[152:153], v[134:135], s[34:35]
	v_pk_mul_f32 v[154:155], v[136:137], s[34:35]
	v_exp_f32_e32 v148, v148
	v_exp_f32_e32 v149, v149
	v_exp_f32_e32 v150, v150
	v_exp_f32_e32 v151, v151
	v_exp_f32_e32 v152, v152
	v_exp_f32_e32 v153, v153
	v_exp_f32_e32 v154, v154
	v_exp_f32_e32 v155, v155
	v_pk_add_f32 v[148:149], v[148:149], 1.0 op_sel_hi:[1,0]
	v_pk_add_f32 v[150:151], v[150:151], 1.0 op_sel_hi:[1,0]
	v_pk_add_f32 v[152:153], v[152:153], 1.0 op_sel_hi:[1,0]
	v_pk_add_f32 v[154:155], v[154:155], 1.0 op_sel_hi:[1,0]
	v_rcp_f32_e32 v148, v148
	v_rcp_f32_e32 v149, v149
	v_rcp_f32_e32 v150, v150
	v_rcp_f32_e32 v151, v151
	v_rcp_f32_e32 v152, v152
	v_rcp_f32_e32 v153, v153
	v_rcp_f32_e32 v154, v154
	v_rcp_f32_e32 v155, v155
	v_pk_mul_f32 v[130:131], v[130:131], v[148:149]
	v_pk_mul_f32 v[132:133], v[132:133], v[150:151]
	v_pk_mul_f32 v[134:135], v[134:135], v[152:153]
	v_pk_mul_f32 v[136:137], v[136:137], v[154:155]
	v_pk_mul_f32 v[130:131], v[130:131], v[138:139]
	v_pk_mul_f32 v[132:133], v[132:133], v[140:141]
	v_pk_mul_f32 v[134:135], v[134:135], v[142:143]
	v_pk_mul_f32 v[136:137], v[136:137], v[144:145]
	v_cvt_pk_bf16_f32 v148, v130, v131
	v_cvt_pk_bf16_f32 v149, v132, v133
	v_cvt_pk_bf16_f32 v150, v134, v135
	v_cvt_pk_bf16_f32 v151, v136, v137
	global_store_dwordx4 v159, v[148:151], s[40:41]
	s_add_u32 s40, s40, 0x2c00
	s_addc_u32 s41, s41, 0
	s_add_i32 s13, s13, 1
	s_cmp_lt_u32 s13, 8
	s_cbranch_scc1 .Lcv_loop
	s_branch .LBB0_17
	s_nop 0
	s_nop 0
	s_nop 0
	s_nop 0
	s_nop 0
	s_nop 0
	s_nop 0
	s_nop 0
	s_nop 0
	s_nop 0
	s_nop 0
	s_nop 0
	s_nop 0
	s_nop 0
	s_nop 0
	s_nop 0
	s_nop 0
	s_nop 0
	s_nop 0
	s_nop 0
	s_nop 0
	s_nop 0
	s_nop 0
	s_nop 0
	s_nop 0
	s_nop 0
	s_nop 0
	s_nop 0
	s_nop 0
	s_nop 0
	s_nop 0
	s_nop 0
	s_nop 0
	s_nop 0
	s_nop 0
	s_nop 0
	s_nop 0
	s_nop 0
	s_nop 0
	s_nop 0
	s_nop 0
	s_nop 0
	s_nop 0
	s_nop 0
	s_nop 0
	s_nop 0
	s_nop 0
	s_nop 0
	s_nop 0
	s_nop 0
	s_nop 0
	s_nop 0
	s_nop 0
	s_nop 0
	s_nop 0
	s_nop 0
	s_nop 0
	s_nop 0
	s_nop 0
	s_nop 0
	s_nop 0
	s_nop 0
	s_nop 0
	s_nop 0
	s_nop 0
	s_nop 0
	s_nop 0
	s_nop 0
	s_nop 0
	s_nop 0
	s_nop 0
	s_nop 0
	s_nop 0
	s_nop 0
	s_nop 0
	s_nop 0
	s_nop 0
	s_nop 0
	s_nop 0
	s_nop 0
	s_nop 0
	s_nop 0
	s_nop 0
	s_nop 0
	s_nop 0
	s_nop 0
	s_nop 0
	s_nop 0
	s_nop 0
	s_nop 0
	s_nop 0
	s_nop 0
	s_nop 0
	s_nop 0
	s_nop 0
	s_nop 0
	s_nop 0
	s_nop 0
	s_nop 0
	s_nop 0
	s_nop 0
	s_nop 0
	s_nop 0
	s_nop 0
	s_nop 0
	s_nop 0
	s_nop 0
	s_nop 0
	s_nop 0
	s_nop 0
	s_nop 0
	s_nop 0
	s_nop 0
	s_nop 0
	s_nop 0
	s_nop 0
	s_nop 0
	s_nop 0
	s_nop 0
	s_nop 0
	s_nop 0
	s_nop 0
	s_nop 0
	s_nop 0
	s_nop 0
	s_nop 0
	s_nop 0
	s_nop 0
	s_nop 0
	s_nop 0
	s_nop 0
	s_nop 0
	s_nop 0
	s_nop 0
	s_nop 0
	s_nop 0
	s_nop 0
	s_nop 0
	s_nop 0
	s_nop 0
	s_nop 0
	s_nop 0
	s_nop 0
	s_nop 0
	s_nop 0
	s_nop 0
	s_nop 0
	s_nop 0
	s_nop 0
	s_nop 0
	s_nop 0
	s_nop 0
	s_nop 0
	s_nop 0
	s_nop 0
	s_nop 0
	s_nop 0
	s_nop 0
	s_nop 0
	s_nop 0
	s_nop 0
	s_nop 0
	s_nop 0
	s_nop 0
	s_nop 0
	s_nop 0
	s_nop 0
	s_nop 0
	s_nop 0
	s_nop 0
	s_nop 0
	s_nop 0
	s_nop 0
	s_nop 0
	s_nop 0
	s_nop 0
	s_nop 0
	s_nop 0
	s_nop 0
	s_nop 0
	s_nop 0
	s_nop 0
	s_nop 0
	s_nop 0
	s_nop 0
	s_nop 0
	s_nop 0
	s_nop 0
	s_nop 0
	s_nop 0
	s_nop 0
	s_nop 0
	s_nop 0
	s_nop 0
	s_nop 0
	s_nop 0
	s_nop 0
	s_nop 0
	s_nop 0
	s_nop 0
	s_nop 0
	s_nop 0
	s_nop 0
	s_nop 0
	s_nop 0
	s_nop 0
	s_nop 0
	s_nop 0
	s_nop 0
	s_nop 0
	s_nop 0
	s_nop 0
	s_nop 0
	s_nop 0
	s_nop 0
	s_nop 0
	s_nop 0
	s_nop 0
	s_nop 0
	s_nop 0
	s_nop 0
	s_nop 0
	s_nop 0
	s_nop 0
	s_nop 0
	s_nop 0
	s_nop 0
	s_nop 0
	s_nop 0
	s_nop 0
	s_nop 0
	s_nop 0
	s_nop 0
	s_nop 0
	s_nop 0
	s_nop 0
	s_nop 0
	s_nop 0
	s_nop 0
	s_nop 0
	s_nop 0
	s_nop 0
	s_nop 0
	s_nop 0
	s_nop 0
	s_nop 0
	s_nop 0
	s_nop 0
	s_nop 0
	s_nop 0
	s_nop 0
	s_nop 0
	s_nop 0
	s_nop 0
	s_nop 0
	s_nop 0
	s_nop 0
	s_nop 0
	s_nop 0
	s_nop 0
	s_nop 0
	s_nop 0
	s_nop 0
	s_nop 0
	s_nop 0
	s_nop 0
	s_nop 0
	s_nop 0
	s_nop 0
	s_nop 0
	s_nop 0
	s_nop 0
	s_nop 0
	s_nop 0
	s_nop 0
	s_nop 0
	s_nop 0
	s_nop 0
	s_nop 0
	s_nop 0
	s_nop 0
	s_nop 0
	s_nop 0
	s_nop 0
	s_nop 0
	s_nop 0
	s_nop 0
	s_nop 0
	s_nop 0
	s_nop 0
	s_nop 0
	s_nop 0
	s_nop 0
	s_nop 0
	s_nop 0
	s_nop 0
	s_nop 0
	s_nop 0
	s_nop 0
	s_nop 0
	s_nop 0
	s_nop 0
	s_nop 0
	s_nop 0
	s_nop 0
	s_nop 0
	s_nop 0
	s_nop 0
	s_nop 0
	s_nop 0
	s_nop 0
	s_nop 0
	s_nop 0
	s_nop 0
	s_nop 0
	s_nop 0
	s_nop 0
	s_nop 0
	s_nop 0
	s_nop 0
	s_nop 0
	s_nop 0
	s_nop 0
	s_nop 0
	s_nop 0
	s_nop 0
	s_nop 0
	s_nop 0
	s_nop 0
	s_nop 0
	s_nop 0
	s_nop 0
	s_nop 0
	s_nop 0
	s_nop 0
	s_nop 0
	s_nop 0
	s_nop 0
	s_nop 0
	s_nop 0
	s_nop 0
	s_nop 0
	s_nop 0
	s_nop 0
	s_nop 0
	s_nop 0
	s_nop 0
	s_nop 0
	s_nop 0
	s_nop 0
	s_nop 0
	s_nop 0
	s_nop 0
	s_nop 0
	s_nop 0
	s_nop 0
	s_nop 0
	s_nop 0
	s_nop 0
	s_nop 0
	s_nop 0
